# w_o skinny tail (layers 1-3) hand-written with four batches of fragment loads in flight
# speedup vs baseline: 1.0293x; 1.0010x over previous
; template <int WHICH>
; __device__ __forceinline__ void skinny_tail(const int TID, const int b0, const Params& p, const int first) {
;     const int lane = TID & 63, wid = TID >> 6, q = lane >> 4;
;     if (wid >= 5) return;
;     for (int b = b0; b < 256; b += (int)gridDim.x) {
;     const int ct = b & 127, rt = (b >> 7) * 5 + wid;
;     const int row = 24576 + rt * 16 + (lane & 15);
;     const int colb = ct * 16 + (lane & 15);
;     ...
;         const bf16_t* A = (const bf16_t*)(p.ws + WS_H) + (size_t)row * D + q * 8; const bf16_t* B = (const bf16_t*)(p.ws + WS_BTO) + (size_t)colb * D + q * 8;
;         float* z = (float*)(p.ws + WS_Z);
;         f32x4 acc = (f32x4){0.f, 0.f, 0.f, 0.f};
;         for (int k0 = 0; k0 < 64; k0 += 8) { bf16x8 av[8], bv[8];
; #pragma unroll
;             for (int i = 0; i < 8; ++i) { av[i] = *(const bf16x8*)(A + (k0 + i) * 32); bv[i] = *(const bf16x8*)(B + (k0 + i) * 32); }
; #pragma unroll
;             for (int i = 0; i < 8; ++i) acc = __builtin_amdgcn_mfma_f32_16x16x32_bf16(av[i], bv[i], acc, 0, 0, 0); }
; #pragma unroll
;         for (int j = 0; j < 4; ++j) { const int tok = 24576 + rt * 16 + q * 4 + j; const float res = first ? src_row(p, tok)[colb] : z[(size_t)tok * D + colb]; z[(size_t)tok * D + colb] = res + acc[j]; }
.LBB0_157:
	s_cmp_eq_u32 s5, 7
	s_cbranch_scc1 .Lt7_orig
	s_cmpk_lg_i32 s96, 0x100
	s_cbranch_scc1 .Lt7_orig
	v_lshrrev_b32_e32 v0, 6, v194
	v_and_b32_e32 v1, 63, v194
	s_nop 0
	v_readfirstlane_b32 s38, v0
	s_cmp_ge_u32 s38, 5
	s_cbranch_scc1 .Lt7_done
	s_lshr_b32 s8, s22, 7
	s_mul_i32 s8, s8, 5
	s_add_i32 s8, s8, s38
	s_and_b32 s9, s22, 127
	v_and_b32_e32 v2, 15, v1
	v_lshrrev_b32_e32 v3, 4, v1
	s_lshl_b32 s10, s8, 4
	s_add_i32 s10, s10, 0x6000
	v_add_u32_e32 v4, s10, v2
	v_lshlrev_b32_e32 v4, 12, v4
	v_lshl_add_u32 v4, v3, 4, v4
	s_lshl_b32 s11, s9, 4
	v_add_u32_e32 v5, s11, v2
	v_lshlrev_b32_e32 v6, 12, v5
	v_lshl_add_u32 v6, v3, 4, v6
	s_add_u32 s40, s94, 0xc200000
	s_addc_u32 s41, s95, 0
	s_add_u32 s42, s94, 0x4c541000
	s_addc_u32 s43, s95, 0
	v_lshl_add_u32 v7, v3, 2, s10
	v_lshlrev_b32_e32 v7, 13, v7
	v_lshl_add_u32 v7, v5, 2, v7
	s_mov_b64 s[44:45], s[94:95]
	global_load_dword v8, v7, s[44:45]
	s_add_u32 s44, s44, 0x2000
	s_addc_u32 s45, s45, 0
	global_load_dword v9, v7, s[44:45]
	s_add_u32 s44, s44, 0x2000
	s_addc_u32 s45, s45, 0
	global_load_dword v10, v7, s[44:45]
	s_add_u32 s44, s44, 0x2000
	s_addc_u32 s45, s45, 0
	global_load_dword v11, v7, s[44:45]
	global_load_dwordx4 v[32:35], v4, s[40:41] offset:0
	global_load_dwordx4 v[36:39], v4, s[40:41] offset:64
	global_load_dwordx4 v[40:43], v4, s[40:41] offset:128
	global_load_dwordx4 v[44:47], v4, s[40:41] offset:192
	global_load_dwordx4 v[48:51], v6, s[42:43] offset:0
	global_load_dwordx4 v[52:55], v6, s[42:43] offset:64
	global_load_dwordx4 v[56:59], v6, s[42:43] offset:128
	global_load_dwordx4 v[60:63], v6, s[42:43] offset:192
	global_load_dwordx4 v[64:67], v4, s[40:41] offset:256
	global_load_dwordx4 v[68:71], v4, s[40:41] offset:320
	global_load_dwordx4 v[72:75], v4, s[40:41] offset:384
	global_load_dwordx4 v[76:79], v4, s[40:41] offset:448
	global_load_dwordx4 v[80:83], v6, s[42:43] offset:256
	global_load_dwordx4 v[84:87], v6, s[42:43] offset:320
	global_load_dwordx4 v[88:91], v6, s[42:43] offset:384
	global_load_dwordx4 v[92:95], v6, s[42:43] offset:448
	global_load_dwordx4 v[96:99], v4, s[40:41] offset:512
	global_load_dwordx4 v[100:103], v4, s[40:41] offset:576
	global_load_dwordx4 v[104:107], v4, s[40:41] offset:640
	global_load_dwordx4 v[108:111], v4, s[40:41] offset:704
	global_load_dwordx4 v[112:115], v6, s[42:43] offset:512
	global_load_dwordx4 v[116:119], v6, s[42:43] offset:576
	global_load_dwordx4 v[120:123], v6, s[42:43] offset:640
	global_load_dwordx4 v[124:127], v6, s[42:43] offset:704
	global_load_dwordx4 v[128:131], v4, s[40:41] offset:768
	global_load_dwordx4 v[132:135], v4, s[40:41] offset:832
	global_load_dwordx4 v[136:139], v4, s[40:41] offset:896
	global_load_dwordx4 v[140:143], v4, s[40:41] offset:960
	global_load_dwordx4 v[144:147], v6, s[42:43] offset:768
	global_load_dwordx4 v[148:151], v6, s[42:43] offset:832
	global_load_dwordx4 v[152:155], v6, s[42:43] offset:896
	global_load_dwordx4 v[156:159], v6, s[42:43] offset:960
	v_mov_b32_e32 v24, 0
	v_mov_b32_e32 v25, 0
	v_mov_b32_e32 v26, 0
	v_mov_b32_e32 v27, 0
	s_waitcnt vmcnt(24)
	v_mfma_f32_16x16x32_bf16 v[24:27], v[32:35], v[48:51], v[24:27]
	v_mfma_f32_16x16x32_bf16 v[24:27], v[36:39], v[52:55], v[24:27]
	v_mfma_f32_16x16x32_bf16 v[24:27], v[40:43], v[56:59], v[24:27]
	v_mfma_f32_16x16x32_bf16 v[24:27], v[44:47], v[60:63], v[24:27]
	global_load_dwordx4 v[32:35], v4, s[40:41] offset:1024
	global_load_dwordx4 v[36:39], v4, s[40:41] offset:1088
	global_load_dwordx4 v[40:43], v4, s[40:41] offset:1152
	global_load_dwordx4 v[44:47], v4, s[40:41] offset:1216
	global_load_dwordx4 v[48:51], v6, s[42:43] offset:1024
	global_load_dwordx4 v[52:55], v6, s[42:43] offset:1088
	global_load_dwordx4 v[56:59], v6, s[42:43] offset:1152
	global_load_dwordx4 v[60:63], v6, s[42:43] offset:1216
	s_waitcnt vmcnt(24)
	v_mfma_f32_16x16x32_bf16 v[24:27], v[64:67], v[80:83], v[24:27]
	v_mfma_f32_16x16x32_bf16 v[24:27], v[68:71], v[84:87], v[24:27]
	v_mfma_f32_16x16x32_bf16 v[24:27], v[72:75], v[88:91], v[24:27]
	v_mfma_f32_16x16x32_bf16 v[24:27], v[76:79], v[92:95], v[24:27]
	global_load_dwordx4 v[64:67], v4, s[40:41] offset:1280
	global_load_dwordx4 v[68:71], v4, s[40:41] offset:1344
	global_load_dwordx4 v[72:75], v4, s[40:41] offset:1408
	global_load_dwordx4 v[76:79], v4, s[40:41] offset:1472
	global_load_dwordx4 v[80:83], v6, s[42:43] offset:1280
	global_load_dwordx4 v[84:87], v6, s[42:43] offset:1344
	global_load_dwordx4 v[88:91], v6, s[42:43] offset:1408
	global_load_dwordx4 v[92:95], v6, s[42:43] offset:1472
	s_waitcnt vmcnt(24)
	v_mfma_f32_16x16x32_bf16 v[24:27], v[96:99], v[112:115], v[24:27]
	v_mfma_f32_16x16x32_bf16 v[24:27], v[100:103], v[116:119], v[24:27]
	v_mfma_f32_16x16x32_bf16 v[24:27], v[104:107], v[120:123], v[24:27]
	v_mfma_f32_16x16x32_bf16 v[24:27], v[108:111], v[124:127], v[24:27]
	global_load_dwordx4 v[96:99], v4, s[40:41] offset:1536
	global_load_dwordx4 v[100:103], v4, s[40:41] offset:1600
	global_load_dwordx4 v[104:107], v4, s[40:41] offset:1664
	global_load_dwordx4 v[108:111], v4, s[40:41] offset:1728
	global_load_dwordx4 v[112:115], v6, s[42:43] offset:1536
	global_load_dwordx4 v[116:119], v6, s[42:43] offset:1600
	global_load_dwordx4 v[120:123], v6, s[42:43] offset:1664
	global_load_dwordx4 v[124:127], v6, s[42:43] offset:1728
	s_waitcnt vmcnt(24)
; template <int WHICH>
; __device__ __forceinline__ void skinny_tail(const int TID, const int b0, const Params& p, const int first) {
;     ...
;         for (int k0 = 0; k0 < 64; k0 += 8) { bf16x8 av[8], bv[8];
; #pragma unroll
;             for (int i = 0; i < 8; ++i) { av[i] = *(const bf16x8*)(A + (k0 + i) * 32); bv[i] = *(const bf16x8*)(B + (k0 + i) * 32); }
; #pragma unroll
;             for (int i = 0; i < 8; ++i) acc = __builtin_amdgcn_mfma_f32_16x16x32_bf16(av[i], bv[i], acc, 0, 0, 0); }
	v_mfma_f32_16x16x32_bf16 v[24:27], v[128:131], v[144:147], v[24:27]
	v_mfma_f32_16x16x32_bf16 v[24:27], v[132:135], v[148:151], v[24:27]
	v_mfma_f32_16x16x32_bf16 v[24:27], v[136:139], v[152:155], v[24:27]
	v_mfma_f32_16x16x32_bf16 v[24:27], v[140:143], v[156:159], v[24:27]
	global_load_dwordx4 v[128:131], v4, s[40:41] offset:1792
	global_load_dwordx4 v[132:135], v4, s[40:41] offset:1856
	global_load_dwordx4 v[136:139], v4, s[40:41] offset:1920
	global_load_dwordx4 v[140:143], v4, s[40:41] offset:1984
	global_load_dwordx4 v[144:147], v6, s[42:43] offset:1792
	global_load_dwordx4 v[148:151], v6, s[42:43] offset:1856
	global_load_dwordx4 v[152:155], v6, s[42:43] offset:1920
	global_load_dwordx4 v[156:159], v6, s[42:43] offset:1984
	s_waitcnt vmcnt(24)
	v_mfma_f32_16x16x32_bf16 v[24:27], v[32:35], v[48:51], v[24:27]
	v_mfma_f32_16x16x32_bf16 v[24:27], v[36:39], v[52:55], v[24:27]
	v_mfma_f32_16x16x32_bf16 v[24:27], v[40:43], v[56:59], v[24:27]
	v_mfma_f32_16x16x32_bf16 v[24:27], v[44:47], v[60:63], v[24:27]
	global_load_dwordx4 v[32:35], v4, s[40:41] offset:2048
	global_load_dwordx4 v[36:39], v4, s[40:41] offset:2112
	global_load_dwordx4 v[40:43], v4, s[40:41] offset:2176
	global_load_dwordx4 v[44:47], v4, s[40:41] offset:2240
	global_load_dwordx4 v[48:51], v6, s[42:43] offset:2048
	global_load_dwordx4 v[52:55], v6, s[42:43] offset:2112
	global_load_dwordx4 v[56:59], v6, s[42:43] offset:2176
	global_load_dwordx4 v[60:63], v6, s[42:43] offset:2240
	s_waitcnt vmcnt(24)
	v_mfma_f32_16x16x32_bf16 v[24:27], v[64:67], v[80:83], v[24:27]
	v_mfma_f32_16x16x32_bf16 v[24:27], v[68:71], v[84:87], v[24:27]
	v_mfma_f32_16x16x32_bf16 v[24:27], v[72:75], v[88:91], v[24:27]
	v_mfma_f32_16x16x32_bf16 v[24:27], v[76:79], v[92:95], v[24:27]
	global_load_dwordx4 v[64:67], v4, s[40:41] offset:2304
	global_load_dwordx4 v[68:71], v4, s[40:41] offset:2368
	global_load_dwordx4 v[72:75], v4, s[40:41] offset:2432
	global_load_dwordx4 v[76:79], v4, s[40:41] offset:2496
	global_load_dwordx4 v[80:83], v6, s[42:43] offset:2304
	global_load_dwordx4 v[84:87], v6, s[42:43] offset:2368
	global_load_dwordx4 v[88:91], v6, s[42:43] offset:2432
	global_load_dwordx4 v[92:95], v6, s[42:43] offset:2496
	s_waitcnt vmcnt(24)
	v_mfma_f32_16x16x32_bf16 v[24:27], v[96:99], v[112:115], v[24:27]
	v_mfma_f32_16x16x32_bf16 v[24:27], v[100:103], v[116:119], v[24:27]
	v_mfma_f32_16x16x32_bf16 v[24:27], v[104:107], v[120:123], v[24:27]
	v_mfma_f32_16x16x32_bf16 v[24:27], v[108:111], v[124:127], v[24:27]
	global_load_dwordx4 v[96:99], v4, s[40:41] offset:2560
	global_load_dwordx4 v[100:103], v4, s[40:41] offset:2624
	global_load_dwordx4 v[104:107], v4, s[40:41] offset:2688
	global_load_dwordx4 v[108:111], v4, s[40:41] offset:2752
	global_load_dwordx4 v[112:115], v6, s[42:43] offset:2560
	global_load_dwordx4 v[116:119], v6, s[42:43] offset:2624
	global_load_dwordx4 v[120:123], v6, s[42:43] offset:2688
	global_load_dwordx4 v[124:127], v6, s[42:43] offset:2752
	s_waitcnt vmcnt(24)
	v_mfma_f32_16x16x32_bf16 v[24:27], v[128:131], v[144:147], v[24:27]
	v_mfma_f32_16x16x32_bf16 v[24:27], v[132:135], v[148:151], v[24:27]
	v_mfma_f32_16x16x32_bf16 v[24:27], v[136:139], v[152:155], v[24:27]
	v_mfma_f32_16x16x32_bf16 v[24:27], v[140:143], v[156:159], v[24:27]
	global_load_dwordx4 v[128:131], v4, s[40:41] offset:2816
	global_load_dwordx4 v[132:135], v4, s[40:41] offset:2880
	global_load_dwordx4 v[136:139], v4, s[40:41] offset:2944
	global_load_dwordx4 v[140:143], v4, s[40:41] offset:3008
	global_load_dwordx4 v[144:147], v6, s[42:43] offset:2816
	global_load_dwordx4 v[148:151], v6, s[42:43] offset:2880
	global_load_dwordx4 v[152:155], v6, s[42:43] offset:2944
	global_load_dwordx4 v[156:159], v6, s[42:43] offset:3008
	s_waitcnt vmcnt(24)
	v_mfma_f32_16x16x32_bf16 v[24:27], v[32:35], v[48:51], v[24:27]
	v_mfma_f32_16x16x32_bf16 v[24:27], v[36:39], v[52:55], v[24:27]
	v_mfma_f32_16x16x32_bf16 v[24:27], v[40:43], v[56:59], v[24:27]
	v_mfma_f32_16x16x32_bf16 v[24:27], v[44:47], v[60:63], v[24:27]
	global_load_dwordx4 v[32:35], v4, s[40:41] offset:3072
	global_load_dwordx4 v[36:39], v4, s[40:41] offset:3136
	global_load_dwordx4 v[40:43], v4, s[40:41] offset:3200
	global_load_dwordx4 v[44:47], v4, s[40:41] offset:3264
	global_load_dwordx4 v[48:51], v6, s[42:43] offset:3072
	global_load_dwordx4 v[52:55], v6, s[42:43] offset:3136
	global_load_dwordx4 v[56:59], v6, s[42:43] offset:3200
	global_load_dwordx4 v[60:63], v6, s[42:43] offset:3264
	s_waitcnt vmcnt(24)
; template <int WHICH>
; __device__ __forceinline__ void skinny_tail(const int TID, const int b0, const Params& p, const int first) {
;     ...
;         for (int k0 = 0; k0 < 64; k0 += 8) { bf16x8 av[8], bv[8];
; #pragma unroll
;             for (int i = 0; i < 8; ++i) { av[i] = *(const bf16x8*)(A + (k0 + i) * 32); bv[i] = *(const bf16x8*)(B + (k0 + i) * 32); }
; #pragma unroll
;             for (int i = 0; i < 8; ++i) acc = __builtin_amdgcn_mfma_f32_16x16x32_bf16(av[i], bv[i], acc, 0, 0, 0); }
; #pragma unroll
;         for (int j = 0; j < 4; ++j) { const int tok = 24576 + rt * 16 + q * 4 + j; const float res = first ? src_row(p, tok)[colb] : z[(size_t)tok * D + colb]; z[(size_t)tok * D + colb] = res + acc[j]; }
	v_mfma_f32_16x16x32_bf16 v[24:27], v[64:67], v[80:83], v[24:27]
	v_mfma_f32_16x16x32_bf16 v[24:27], v[68:71], v[84:87], v[24:27]
	v_mfma_f32_16x16x32_bf16 v[24:27], v[72:75], v[88:91], v[24:27]
	v_mfma_f32_16x16x32_bf16 v[24:27], v[76:79], v[92:95], v[24:27]
	global_load_dwordx4 v[64:67], v4, s[40:41] offset:3328
	global_load_dwordx4 v[68:71], v4, s[40:41] offset:3392
	global_load_dwordx4 v[72:75], v4, s[40:41] offset:3456
	global_load_dwordx4 v[76:79], v4, s[40:41] offset:3520
	global_load_dwordx4 v[80:83], v6, s[42:43] offset:3328
	global_load_dwordx4 v[84:87], v6, s[42:43] offset:3392
	global_load_dwordx4 v[88:91], v6, s[42:43] offset:3456
	global_load_dwordx4 v[92:95], v6, s[42:43] offset:3520
	s_waitcnt vmcnt(24)
	v_mfma_f32_16x16x32_bf16 v[24:27], v[96:99], v[112:115], v[24:27]
	v_mfma_f32_16x16x32_bf16 v[24:27], v[100:103], v[116:119], v[24:27]
	v_mfma_f32_16x16x32_bf16 v[24:27], v[104:107], v[120:123], v[24:27]
	v_mfma_f32_16x16x32_bf16 v[24:27], v[108:111], v[124:127], v[24:27]
	global_load_dwordx4 v[96:99], v4, s[40:41] offset:3584
	global_load_dwordx4 v[100:103], v4, s[40:41] offset:3648
	global_load_dwordx4 v[104:107], v4, s[40:41] offset:3712
	global_load_dwordx4 v[108:111], v4, s[40:41] offset:3776
	global_load_dwordx4 v[112:115], v6, s[42:43] offset:3584
	global_load_dwordx4 v[116:119], v6, s[42:43] offset:3648
	global_load_dwordx4 v[120:123], v6, s[42:43] offset:3712
	global_load_dwordx4 v[124:127], v6, s[42:43] offset:3776
	s_waitcnt vmcnt(24)
	v_mfma_f32_16x16x32_bf16 v[24:27], v[128:131], v[144:147], v[24:27]
	v_mfma_f32_16x16x32_bf16 v[24:27], v[132:135], v[148:151], v[24:27]
	v_mfma_f32_16x16x32_bf16 v[24:27], v[136:139], v[152:155], v[24:27]
	v_mfma_f32_16x16x32_bf16 v[24:27], v[140:143], v[156:159], v[24:27]
	global_load_dwordx4 v[128:131], v4, s[40:41] offset:3840
	global_load_dwordx4 v[132:135], v4, s[40:41] offset:3904
	global_load_dwordx4 v[136:139], v4, s[40:41] offset:3968
	global_load_dwordx4 v[140:143], v4, s[40:41] offset:4032
	global_load_dwordx4 v[144:147], v6, s[42:43] offset:3840
	global_load_dwordx4 v[148:151], v6, s[42:43] offset:3904
	global_load_dwordx4 v[152:155], v6, s[42:43] offset:3968
	global_load_dwordx4 v[156:159], v6, s[42:43] offset:4032
	s_waitcnt vmcnt(24)
	v_mfma_f32_16x16x32_bf16 v[24:27], v[32:35], v[48:51], v[24:27]
	v_mfma_f32_16x16x32_bf16 v[24:27], v[36:39], v[52:55], v[24:27]
	v_mfma_f32_16x16x32_bf16 v[24:27], v[40:43], v[56:59], v[24:27]
	v_mfma_f32_16x16x32_bf16 v[24:27], v[44:47], v[60:63], v[24:27]
	s_waitcnt vmcnt(16)
	v_mfma_f32_16x16x32_bf16 v[24:27], v[64:67], v[80:83], v[24:27]
	v_mfma_f32_16x16x32_bf16 v[24:27], v[68:71], v[84:87], v[24:27]
	v_mfma_f32_16x16x32_bf16 v[24:27], v[72:75], v[88:91], v[24:27]
	v_mfma_f32_16x16x32_bf16 v[24:27], v[76:79], v[92:95], v[24:27]
	s_waitcnt vmcnt(8)
	v_mfma_f32_16x16x32_bf16 v[24:27], v[96:99], v[112:115], v[24:27]
	v_mfma_f32_16x16x32_bf16 v[24:27], v[100:103], v[116:119], v[24:27]
	v_mfma_f32_16x16x32_bf16 v[24:27], v[104:107], v[120:123], v[24:27]
	v_mfma_f32_16x16x32_bf16 v[24:27], v[108:111], v[124:127], v[24:27]
	s_waitcnt vmcnt(0)
	v_mfma_f32_16x16x32_bf16 v[24:27], v[128:131], v[144:147], v[24:27]
	v_mfma_f32_16x16x32_bf16 v[24:27], v[132:135], v[148:151], v[24:27]
	v_mfma_f32_16x16x32_bf16 v[24:27], v[136:139], v[152:155], v[24:27]
	v_mfma_f32_16x16x32_bf16 v[24:27], v[140:143], v[156:159], v[24:27]
	s_nop 7
	s_nop 3
	s_mov_b64 s[44:45], s[94:95]
	v_add_f32_e32 v8, v8, v24
	global_store_dword v7, v8, s[44:45]
	s_add_u32 s44, s44, 0x2000
	s_addc_u32 s45, s45, 0
	v_add_f32_e32 v9, v9, v25
	global_store_dword v7, v9, s[44:45]
	s_add_u32 s44, s44, 0x2000
	s_addc_u32 s45, s45, 0
	v_add_f32_e32 v10, v10, v26
	global_store_dword v7, v10, s[44:45]
	s_add_u32 s44, s44, 0x2000
	s_addc_u32 s45, s45, 0
	v_add_f32_e32 v11, v11, v27
	global_store_dword v7, v11, s[44:45]
.Lt7_done:
	s_mov_b64 s[0:1], 0
	s_branch .LBB0_225
